# streaming (nt) loads for read-once f32 data: V table rows in PRO, the f32 residual in the Fourier w_o epilogue (keep the cache for what later phases re-read)
# speedup vs baseline: 1.0091x; 1.0086x over previous
.LBB0_85:
	s_and_b64 vcc, exec, s[14:15]
	s_cbranch_vccnz .LBB0_84
	s_lshl_b32 s28, s16, 25
	s_lshl_b64 s[42:43], s[28:29], 2
	s_add_u32 s84, s62, s42
	s_addc_u32 s85, s63, s43
	s_add_u32 s17, s64, s42
	s_addc_u32 s28, s65, s43
	s_sub_u32 s42, s17, s84
	s_subb_u32 s43, s28, s85
	s_ashr_i64 s[42:43], s[42:43], 2
	s_and_b64 s[44:45], s[34:35], exec
	s_brev_b32 s17, 16
	s_cselect_b32 s17, s17, 0x10000000
	s_add_u32 s86, s54, s17
	s_addc_u32 s87, s55, 0
	s_lshl_b32 s28, s16, 15
	s_lshl_b64 s[44:45], s[28:29], 2
	s_add_u32 s88, s74, s44
	s_addc_u32 s89, s75, s45
	s_lshl_b32 s28, s16, 11
	s_lshl_b64 s[16:17], s[28:29], 2
	s_add_u32 s16, s40, s16
	s_addc_u32 s17, s41, s17
	s_and_b64 s[44:45], s[30:31], exec
	s_cselect_b32 s45, 0, s43
	s_cselect_b32 s44, 0, s42
	s_lshl_b64 s[44:45], s[44:45], 2
	s_add_u32 s28, s84, s44
	s_addc_u32 s39, s85, s45
	s_add_u32 s28, s28, s79
	s_addc_u32 s39, s39, 0
	s_add_u32 s44, s28, s80
	s_addc_u32 s45, s39, 0
	s_waitcnt vmcnt(18)
	v_lshl_add_u64 v[14:15], s[44:45], 0, v[72:73]
	s_and_b64 s[44:45], s[26:27], exec
	s_cselect_b32 s45, 0, s43
	s_cselect_b32 s44, 0, s42
	s_lshl_b64 s[44:45], s[44:45], 2
	s_add_u32 s28, s84, s44
	s_addc_u32 s39, s85, s45
	s_add_u32 s28, s28, s81
	s_addc_u32 s39, s39, 0
	s_add_u32 s44, s28, s82
	s_addc_u32 s45, s39, 0
	global_load_dwordx4 v[2:5], v[14:15], off offset:3072 nt
	global_load_dwordx4 v[6:9], v[14:15], off offset:2048 nt
	global_load_dwordx4 v[10:13], v[14:15], off offset:1024 nt
	global_load_dwordx4 v[46:49], v[14:15], off nt
	v_lshl_add_u64 v[14:15], s[44:45], 0, v[72:73]
	global_load_dwordx4 v[50:53], v[14:15], off offset:3072 nt
	global_load_dwordx4 v[54:57], v[14:15], off offset:2048 nt
	global_load_dwordx4 v[58:61], v[14:15], off offset:1024 nt
	global_load_dwordx4 v[62:65], v[14:15], off nt
	v_lshl_add_u64 v[14:15], s[16:17], 0, v[72:73]
	s_add_u32 s16, s16, s38
	s_mov_b32 s39, s29
	s_addc_u32 s17, s17, 0
	v_lshl_add_u64 v[80:81], v[14:15], 0, s[38:39]
	v_lshl_add_u64 v[82:83], s[16:17], 0, v[72:73]
	global_load_dwordx4 v[140:143], v[80:81], off nt
	global_load_dwordx4 v[144:147], v[82:83], off offset:1024 nt
	global_load_dwordx4 v[148:151], v[82:83], off offset:2048 nt
	global_load_dwordx4 v[152:155], v[82:83], off offset:3072 nt
	v_readlane_b32 s28, v248, 3
	s_add_i32 s28, s28, 0x8000
	s_branch .LBB0_88

.LBB0_88:
	s_add_i32 s39, s0, s28
	s_add_i32 s16, s78, s28
	s_add_i32 s44, s76, s28
	s_cmp_lt_i32 s16, 0x10000
	s_cselect_b32 s45, s16, s39
	s_ashr_i32 s46, s45, 1
	s_cmpk_gt_i32 s46, 0x3fff
	s_cselect_b32 s17, s43, 0
	s_cselect_b32 s16, s42, 0
	s_lshl_b64 s[16:17], s[16:17], 2
	s_add_u32 s16, s84, s16
	s_addc_u32 s17, s85, s17
	s_lshl_b32 s46, s46, 13
	s_and_b32 s46, s46, 0x7ffe000
	s_add_u32 s16, s16, s46
	s_addc_u32 s17, s17, 0
	s_lshl_b32 s45, s45, 12
	s_and_b32 s45, s45, 0x1000
	s_add_u32 s16, s16, s45
	s_addc_u32 s17, s17, 0
	s_cmp_lt_i32 s44, 0x10000
	s_cselect_b32 s44, s44, s39
	s_ashr_i32 s45, s44, 1
	s_cmpk_gt_i32 s45, 0x3fff
	s_waitcnt vmcnt(14)
	v_lshl_add_u64 v[26:27], s[16:17], 0, v[72:73]
	s_cselect_b32 s17, s43, 0
	s_cselect_b32 s16, s42, 0
	s_lshl_b64 s[16:17], s[16:17], 2
	s_add_u32 s16, s84, s16
	s_addc_u32 s17, s85, s17
	s_lshl_b32 s45, s45, 13
	s_and_b32 s45, s45, 0x7ffe000
	s_add_u32 s16, s16, s45
	s_addc_u32 s17, s17, 0
	s_lshl_b32 s44, s44, 12
	s_and_b32 s44, s44, 0x1000
	s_add_u32 s16, s16, s44
	s_addc_u32 s17, s17, 0
	v_lshl_add_u64 v[42:43], s[16:17], 0, v[72:73]
	global_load_dwordx4 v[14:17], v[26:27], off nt
	global_load_dwordx4 v[18:21], v[26:27], off offset:1024 nt
	global_load_dwordx4 v[22:25], v[26:27], off offset:2048 nt
	s_nop 0
	global_load_dwordx4 v[26:29], v[26:27], off offset:3072 nt
	s_nop 0
	global_load_dwordx4 v[30:33], v[42:43], off nt
	global_load_dwordx4 v[34:37], v[42:43], off offset:1024 nt
	global_load_dwordx4 v[38:41], v[42:43], off offset:2048 nt
	s_nop 0
	global_load_dwordx4 v[42:45], v[42:43], off offset:3072 nt
	s_ashr_i32 s16, s39, 1
	s_cmpk_lt_i32 s16, 0x4000
	s_cselect_b64 s[46:47], -1, 0
	s_cmpk_gt_i32 s16, 0x3fff
	s_cselect_b64 s[44:45], -1, 0
	s_and_b64 vcc, exec, s[44:45]
	s_cbranch_vccnz .LBB0_92
	s_waitcnt vmcnt(8)
	v_pk_mul_f32 v[64:65], v[64:65], v[142:143]
	v_pk_mul_f32 v[62:63], v[62:63], v[140:141]
	v_cndmask_b32_e64 v84, 0, 1, s[46:47]
	v_cmp_ne_u32_e64 s[16:17], 1, v84
	s_andn2_b64 vcc, exec, s[46:47]
	s_cbranch_vccz .LBB0_93

.LBB0_388:
	v_lshl_add_u32 v188, s34, 8, v137
	v_lshlrev_b32_e32 v253, 2, v188
	v_lshlrev_b32_e32 v188, 11, v188
	v_lshl_add_u32 v188, s30, 8, v188
	v_or_b32_e32 v252, v188, v136
	v_lshlrev_b32_e32 v251, 1, v252
	v_lshlrev_b32_e32 v250, 2, v252
	v_xor_b32_e32 v254, 16, v167
	v_xor_b32_e32 v255, 32, v167
	v_lshlrev_b32_e32 v254, 2, v254
	v_lshlrev_b32_e32 v255, 2, v255
	v_mov_b32_e32 v192, v250
	global_load_dwordx4 v[204:207], v192, s[36:37] offset:0 nt
	global_load_dwordx4 v[208:211], v192, s[36:37] offset:16 nt
	global_load_dwordx4 v[212:215], v192, s[36:37] offset:512 nt
	global_load_dwordx4 v[216:219], v192, s[36:37] offset:528 nt
	v_add_u32_e32 v192, 0x20000, v250
	global_load_dwordx4 v[220:223], v192, s[36:37] offset:0 nt
	global_load_dwordx4 v[224:227], v192, s[36:37] offset:16 nt
	global_load_dwordx4 v[228:231], v192, s[36:37] offset:512 nt
	global_load_dwordx4 v[232:235], v192, s[36:37] offset:528 nt
	v_add_u32_e32 v192, 0x40000, v250
	global_load_dwordx4 v[236:239], v192, s[36:37] offset:0 nt
	global_load_dwordx4 v[240:243], v192, s[36:37] offset:16 nt
	global_load_dwordx4 v[244:247], v192, s[36:37] offset:512 nt
	global_load_dwordx4 v[168:171], v192, s[36:37] offset:528 nt
	v_add_u32_e32 v192, 0x60000, v250
	global_load_dwordx4 v[172:175], v192, s[36:37] offset:0 nt
	global_load_dwordx4 v[176:179], v192, s[36:37] offset:16 nt
	global_load_dwordx4 v[180:183], v192, s[36:37] offset:512 nt
	global_load_dwordx4 v[184:187], v192, s[36:37] offset:528 nt
	s_waitcnt vmcnt(14)
	v_pk_add_f32 v[124:125], v[124:125], v[204:205]
	v_pk_add_f32 v[126:127], v[126:127], v[206:207]
	v_pk_add_f32 v[120:121], v[120:121], v[208:209]
	v_pk_add_f32 v[122:123], v[122:123], v[210:211]
	v_cvt_pk_bf16_f32 v188, v124, v125
	v_cvt_pk_bf16_f32 v189, v126, v127
	v_cvt_pk_bf16_f32 v190, v120, v121
	v_cvt_pk_bf16_f32 v191, v122, v123
	v_cvt_pk_fp8_f32 v192, v124, v125
	v_cvt_pk_fp8_f32 v193, v120, v121
	v_cvt_pk_fp8_f32 v192, v126, v127 op_sel:[0,0,1]
	v_cvt_pk_fp8_f32 v193, v122, v123 op_sel:[0,0,1]
	v_mov_b32_e32 v204, v251
	v_mov_b32_e32 v205, v252
	global_store_dwordx4 v204, v[188:191], s[68:69] offset:0
	global_store_dwordx2 v205, v[192:193], s[14:15] offset:0
	v_mul_f32_e32 v125, v125, v125
	v_mul_f32_e32 v127, v127, v127
	v_mul_f32_e32 v121, v121, v121
	v_mul_f32_e32 v123, v123, v123
	v_fmac_f32_e32 v125, v124, v124
	v_fmac_f32_e32 v127, v126, v126
	v_fmac_f32_e32 v121, v120, v120
	v_fmac_f32_e32 v123, v122, v122
	v_add_f32_e32 v125, v125, v127
	v_add_f32_e32 v125, v125, v121
	v_add_f32_e32 v194, v123, v125
	s_waitcnt vmcnt(14)
	v_pk_add_f32 v[116:117], v[116:117], v[212:213]
	v_pk_add_f32 v[118:119], v[118:119], v[214:215]
	v_pk_add_f32 v[112:113], v[112:113], v[216:217]
	v_pk_add_f32 v[114:115], v[114:115], v[218:219]
	v_cvt_pk_bf16_f32 v188, v116, v117
	v_cvt_pk_bf16_f32 v189, v118, v119
	v_cvt_pk_bf16_f32 v190, v112, v113
	v_cvt_pk_bf16_f32 v191, v114, v115
	v_cvt_pk_fp8_f32 v192, v116, v117
	v_cvt_pk_fp8_f32 v193, v112, v113
	v_cvt_pk_fp8_f32 v192, v118, v119 op_sel:[0,0,1]
	v_cvt_pk_fp8_f32 v193, v114, v115 op_sel:[0,0,1]
	v_mov_b32_e32 v212, v251
	v_mov_b32_e32 v213, v252
	global_store_dwordx4 v212, v[188:191], s[68:69] offset:256
	global_store_dwordx2 v213, v[192:193], s[14:15] offset:128
	v_mul_f32_e32 v117, v117, v117
	v_mul_f32_e32 v119, v119, v119
	v_mul_f32_e32 v113, v113, v113
	v_mul_f32_e32 v115, v115, v115
	v_fmac_f32_e32 v117, v116, v116
	v_fmac_f32_e32 v119, v118, v118
	v_fmac_f32_e32 v113, v112, v112
	v_fmac_f32_e32 v115, v114, v114
	v_add_f32_e32 v117, v117, v119
	v_add_f32_e32 v117, v117, v113
	v_add_f32_e32 v117, v115, v117
	v_add_f32_e32 v194, v194, v117
	v_add_u32_e32 v192, 0x100000, v250
	global_load_dwordx4 v[204:207], v192, s[36:37] offset:0 nt
	global_load_dwordx4 v[208:211], v192, s[36:37] offset:16 nt
	global_load_dwordx4 v[212:215], v192, s[36:37] offset:512 nt
	global_load_dwordx4 v[216:219], v192, s[36:37] offset:528 nt
	s_waitcnt vmcnt(18)
	v_pk_add_f32 v[108:109], v[108:109], v[220:221]
	v_pk_add_f32 v[110:111], v[110:111], v[222:223]
	v_pk_add_f32 v[104:105], v[104:105], v[224:225]
	v_pk_add_f32 v[106:107], v[106:107], v[226:227]
	v_cvt_pk_bf16_f32 v188, v108, v109
	v_cvt_pk_bf16_f32 v189, v110, v111
	v_cvt_pk_bf16_f32 v190, v104, v105
	v_cvt_pk_bf16_f32 v191, v106, v107
	v_cvt_pk_fp8_f32 v192, v108, v109
	v_cvt_pk_fp8_f32 v193, v104, v105
	v_cvt_pk_fp8_f32 v192, v110, v111 op_sel:[0,0,1]
	v_cvt_pk_fp8_f32 v193, v106, v107 op_sel:[0,0,1]
	v_add_u32_e32 v220, 0x10000, v251
	v_add_u32_e32 v221, 0x8000, v252
	global_store_dwordx4 v220, v[188:191], s[68:69] offset:0
	global_store_dwordx2 v221, v[192:193], s[14:15] offset:0
	v_mul_f32_e32 v109, v109, v109
	v_mul_f32_e32 v111, v111, v111
	v_mul_f32_e32 v105, v105, v105
	v_mul_f32_e32 v107, v107, v107
	v_fmac_f32_e32 v109, v108, v108
	v_fmac_f32_e32 v111, v110, v110
	v_fmac_f32_e32 v105, v104, v104
	v_fmac_f32_e32 v107, v106, v106
	v_add_f32_e32 v109, v109, v111
	v_add_f32_e32 v109, v109, v105
	v_add_f32_e32 v195, v107, v109
	s_waitcnt vmcnt(18)
	v_pk_add_f32 v[100:101], v[100:101], v[228:229]
	v_pk_add_f32 v[102:103], v[102:103], v[230:231]
	v_pk_add_f32 v[96:97], v[96:97], v[232:233]
	v_pk_add_f32 v[98:99], v[98:99], v[234:235]
	v_cvt_pk_bf16_f32 v188, v100, v101
	v_cvt_pk_bf16_f32 v189, v102, v103
	v_cvt_pk_bf16_f32 v190, v96, v97
	v_cvt_pk_bf16_f32 v191, v98, v99
	v_cvt_pk_fp8_f32 v192, v100, v101
	v_cvt_pk_fp8_f32 v193, v96, v97
	v_cvt_pk_fp8_f32 v192, v102, v103 op_sel:[0,0,1]
	v_cvt_pk_fp8_f32 v193, v98, v99 op_sel:[0,0,1]
	v_add_u32_e32 v228, 0x10000, v251
	v_add_u32_e32 v229, 0x8000, v252
	global_store_dwordx4 v228, v[188:191], s[68:69] offset:256
	global_store_dwordx2 v229, v[192:193], s[14:15] offset:128
	v_mul_f32_e32 v101, v101, v101
	v_mul_f32_e32 v103, v103, v103
	v_mul_f32_e32 v97, v97, v97
	v_mul_f32_e32 v99, v99, v99
	v_fmac_f32_e32 v101, v100, v100
	v_fmac_f32_e32 v103, v102, v102
	v_fmac_f32_e32 v97, v96, v96
	v_fmac_f32_e32 v99, v98, v98
	v_add_f32_e32 v101, v101, v103
	v_add_f32_e32 v101, v101, v97
	v_add_f32_e32 v101, v99, v101
	v_add_f32_e32 v195, v195, v101
	v_add_u32_e32 v192, 0x120000, v250
	global_load_dwordx4 v[220:223], v192, s[36:37] offset:0 nt
	global_load_dwordx4 v[224:227], v192, s[36:37] offset:16 nt
	global_load_dwordx4 v[228:231], v192, s[36:37] offset:512 nt
	global_load_dwordx4 v[232:235], v192, s[36:37] offset:528 nt
	s_waitcnt vmcnt(22)
	v_pk_add_f32 v[92:93], v[92:93], v[236:237]
	v_pk_add_f32 v[94:95], v[94:95], v[238:239]
	v_pk_add_f32 v[88:89], v[88:89], v[240:241]
	v_pk_add_f32 v[90:91], v[90:91], v[242:243]
	v_cvt_pk_bf16_f32 v188, v92, v93
	v_cvt_pk_bf16_f32 v189, v94, v95
	v_cvt_pk_bf16_f32 v190, v88, v89
	v_cvt_pk_bf16_f32 v191, v90, v91
	v_cvt_pk_fp8_f32 v192, v92, v93
	v_cvt_pk_fp8_f32 v193, v88, v89
	v_cvt_pk_fp8_f32 v192, v94, v95 op_sel:[0,0,1]
	v_cvt_pk_fp8_f32 v193, v90, v91 op_sel:[0,0,1]
	v_add_u32_e32 v236, 0x20000, v251
	v_add_u32_e32 v237, 0x10000, v252
	global_store_dwordx4 v236, v[188:191], s[68:69] offset:0
	global_store_dwordx2 v237, v[192:193], s[14:15] offset:0
	v_mul_f32_e32 v93, v93, v93
	v_mul_f32_e32 v95, v95, v95
	v_mul_f32_e32 v89, v89, v89
	v_mul_f32_e32 v91, v91, v91
	v_fmac_f32_e32 v93, v92, v92
	v_fmac_f32_e32 v95, v94, v94
	v_fmac_f32_e32 v89, v88, v88
	v_fmac_f32_e32 v91, v90, v90
	v_add_f32_e32 v93, v93, v95
	v_add_f32_e32 v93, v93, v89
	v_add_f32_e32 v196, v91, v93
	s_waitcnt vmcnt(22)
	v_pk_add_f32 v[84:85], v[84:85], v[244:245]
	v_pk_add_f32 v[86:87], v[86:87], v[246:247]
	v_pk_add_f32 v[80:81], v[80:81], v[168:169]
	v_pk_add_f32 v[82:83], v[82:83], v[170:171]
	v_cvt_pk_bf16_f32 v188, v84, v85
	v_cvt_pk_bf16_f32 v189, v86, v87
	v_cvt_pk_bf16_f32 v190, v80, v81
	v_cvt_pk_bf16_f32 v191, v82, v83
	v_cvt_pk_fp8_f32 v192, v84, v85
	v_cvt_pk_fp8_f32 v193, v80, v81
	v_cvt_pk_fp8_f32 v192, v86, v87 op_sel:[0,0,1]
	v_cvt_pk_fp8_f32 v193, v82, v83 op_sel:[0,0,1]
	v_add_u32_e32 v244, 0x20000, v251
	v_add_u32_e32 v245, 0x10000, v252
	global_store_dwordx4 v244, v[188:191], s[68:69] offset:256
	global_store_dwordx2 v245, v[192:193], s[14:15] offset:128
	v_mul_f32_e32 v85, v85, v85
	v_mul_f32_e32 v87, v87, v87
	v_mul_f32_e32 v81, v81, v81
	v_mul_f32_e32 v83, v83, v83
	v_fmac_f32_e32 v85, v84, v84
	v_fmac_f32_e32 v87, v86, v86
	v_fmac_f32_e32 v81, v80, v80
	v_fmac_f32_e32 v83, v82, v82
	v_add_f32_e32 v85, v85, v87
	v_add_f32_e32 v85, v85, v81
	v_add_f32_e32 v85, v83, v85
	v_add_f32_e32 v196, v196, v85
	v_add_u32_e32 v192, 0x140000, v250
	global_load_dwordx4 v[236:239], v192, s[36:37] offset:0 nt
	global_load_dwordx4 v[240:243], v192, s[36:37] offset:16 nt
	global_load_dwordx4 v[244:247], v192, s[36:37] offset:512 nt
	global_load_dwordx4 v[168:171], v192, s[36:37] offset:528 nt
	s_waitcnt vmcnt(26)
	v_pk_add_f32 v[76:77], v[76:77], v[172:173]
	v_pk_add_f32 v[78:79], v[78:79], v[174:175]
	v_pk_add_f32 v[72:73], v[72:73], v[176:177]
	v_pk_add_f32 v[74:75], v[74:75], v[178:179]
	v_cvt_pk_bf16_f32 v188, v76, v77
	v_cvt_pk_bf16_f32 v189, v78, v79
	v_cvt_pk_bf16_f32 v190, v72, v73
	v_cvt_pk_bf16_f32 v191, v74, v75
	v_cvt_pk_fp8_f32 v192, v76, v77
	v_cvt_pk_fp8_f32 v193, v72, v73
	v_cvt_pk_fp8_f32 v192, v78, v79 op_sel:[0,0,1]
	v_cvt_pk_fp8_f32 v193, v74, v75 op_sel:[0,0,1]
	v_add_u32_e32 v172, 0x30000, v251
	v_add_u32_e32 v173, 0x18000, v252
	global_store_dwordx4 v172, v[188:191], s[68:69] offset:0
	global_store_dwordx2 v173, v[192:193], s[14:15] offset:0
	v_mul_f32_e32 v77, v77, v77
	v_mul_f32_e32 v79, v79, v79
	v_mul_f32_e32 v73, v73, v73
	v_mul_f32_e32 v75, v75, v75
	v_fmac_f32_e32 v77, v76, v76
	v_fmac_f32_e32 v79, v78, v78
	v_fmac_f32_e32 v73, v72, v72
	v_fmac_f32_e32 v75, v74, v74
	v_add_f32_e32 v77, v77, v79
	v_add_f32_e32 v77, v77, v73
	v_add_f32_e32 v249, v75, v77
	s_waitcnt vmcnt(26)
	v_pk_add_f32 v[68:69], v[68:69], v[180:181]
	v_pk_add_f32 v[70:71], v[70:71], v[182:183]
	v_pk_add_f32 v[64:65], v[64:65], v[184:185]
	v_pk_add_f32 v[66:67], v[66:67], v[186:187]
	v_cvt_pk_bf16_f32 v188, v68, v69
	v_cvt_pk_bf16_f32 v189, v70, v71
	v_cvt_pk_bf16_f32 v190, v64, v65
	v_cvt_pk_bf16_f32 v191, v66, v67
	v_cvt_pk_fp8_f32 v192, v68, v69
	v_cvt_pk_fp8_f32 v193, v64, v65
	v_cvt_pk_fp8_f32 v192, v70, v71 op_sel:[0,0,1]
	v_cvt_pk_fp8_f32 v193, v66, v67 op_sel:[0,0,1]
	v_add_u32_e32 v180, 0x30000, v251
	v_add_u32_e32 v181, 0x18000, v252
	global_store_dwordx4 v180, v[188:191], s[68:69] offset:256
	global_store_dwordx2 v181, v[192:193], s[14:15] offset:128
	v_mul_f32_e32 v69, v69, v69
	v_mul_f32_e32 v71, v71, v71
	v_mul_f32_e32 v65, v65, v65
	v_mul_f32_e32 v67, v67, v67
	v_fmac_f32_e32 v69, v68, v68
	v_fmac_f32_e32 v71, v70, v70
	v_fmac_f32_e32 v65, v64, v64
	v_fmac_f32_e32 v67, v66, v66
	v_add_f32_e32 v69, v69, v71
	v_add_f32_e32 v69, v69, v65
	v_add_f32_e32 v69, v67, v69
	v_add_f32_e32 v249, v249, v69
	v_add_u32_e32 v192, 0x160000, v250
	global_load_dwordx4 v[172:175], v192, s[36:37] offset:0 nt
	global_load_dwordx4 v[176:179], v192, s[36:37] offset:16 nt
	global_load_dwordx4 v[180:183], v192, s[36:37] offset:512 nt
	global_load_dwordx4 v[184:187], v192, s[36:37] offset:528 nt
	ds_bpermute_b32 v188, v254, v194
	ds_bpermute_b32 v189, v254, v195
	ds_bpermute_b32 v190, v254, v196
	ds_bpermute_b32 v191, v254, v249
	s_waitcnt lgkmcnt(0)
	v_add_f32_e32 v194, v194, v188
	v_add_f32_e32 v195, v195, v189
	v_add_f32_e32 v196, v196, v190
	v_add_f32_e32 v249, v249, v191
	ds_bpermute_b32 v188, v255, v194
	ds_bpermute_b32 v189, v255, v195
	ds_bpermute_b32 v190, v255, v196
	ds_bpermute_b32 v191, v255, v249
	s_waitcnt lgkmcnt(0)
	v_add_f32_e32 v194, v194, v188
	v_add_f32_e32 v195, v195, v189
	v_add_f32_e32 v196, v196, v190
	v_add_f32_e32 v249, v249, v191
	s_and_saveexec_b64 s[30:31], s[4:5]
	global_atomic_add_f32 v253, v194, s[12:13] offset:0
	global_atomic_add_f32 v253, v195, s[12:13] offset:64
	global_atomic_add_f32 v253, v196, s[12:13] offset:128
	global_atomic_add_f32 v253, v249, s[12:13] offset:192
	s_or_b64 exec, exec, s[30:31]
	s_waitcnt vmcnt(30)
	v_pk_add_f32 v[60:61], v[60:61], v[204:205]
	v_pk_add_f32 v[62:63], v[62:63], v[206:207]
	v_pk_add_f32 v[56:57], v[56:57], v[208:209]
	v_pk_add_f32 v[58:59], v[58:59], v[210:211]
	v_cvt_pk_bf16_f32 v188, v60, v61
	v_cvt_pk_bf16_f32 v189, v62, v63
	v_cvt_pk_bf16_f32 v190, v56, v57
	v_cvt_pk_bf16_f32 v191, v58, v59
	v_cvt_pk_fp8_f32 v192, v60, v61
	v_cvt_pk_fp8_f32 v193, v56, v57
	v_cvt_pk_fp8_f32 v192, v62, v63 op_sel:[0,0,1]
	v_cvt_pk_fp8_f32 v193, v58, v59 op_sel:[0,0,1]
	v_add_u32_e32 v204, 0x80000, v251
	v_add_u32_e32 v205, 0x40000, v252
	global_store_dwordx4 v204, v[188:191], s[68:69] offset:0
	global_store_dwordx2 v205, v[192:193], s[14:15] offset:0
	v_mul_f32_e32 v61, v61, v61
	v_mul_f32_e32 v63, v63, v63
	v_mul_f32_e32 v57, v57, v57
	v_mul_f32_e32 v59, v59, v59
	v_fmac_f32_e32 v61, v60, v60
	v_fmac_f32_e32 v63, v62, v62
	v_fmac_f32_e32 v57, v56, v56
	v_fmac_f32_e32 v59, v58, v58
	v_add_f32_e32 v61, v61, v63
	v_add_f32_e32 v61, v61, v57
	v_add_f32_e32 v194, v59, v61
	s_waitcnt vmcnt(30)
	v_pk_add_f32 v[52:53], v[52:53], v[212:213]
	v_pk_add_f32 v[54:55], v[54:55], v[214:215]
	v_pk_add_f32 v[48:49], v[48:49], v[216:217]
	v_pk_add_f32 v[50:51], v[50:51], v[218:219]
	v_cvt_pk_bf16_f32 v188, v52, v53
	v_cvt_pk_bf16_f32 v189, v54, v55
	v_cvt_pk_bf16_f32 v190, v48, v49
	v_cvt_pk_bf16_f32 v191, v50, v51
	v_cvt_pk_fp8_f32 v192, v52, v53
	v_cvt_pk_fp8_f32 v193, v48, v49
	v_cvt_pk_fp8_f32 v192, v54, v55 op_sel:[0,0,1]
	v_cvt_pk_fp8_f32 v193, v50, v51 op_sel:[0,0,1]
	v_add_u32_e32 v212, 0x80000, v251
	v_add_u32_e32 v213, 0x40000, v252
	global_store_dwordx4 v212, v[188:191], s[68:69] offset:256
	global_store_dwordx2 v213, v[192:193], s[14:15] offset:128
	v_mul_f32_e32 v53, v53, v53
	v_mul_f32_e32 v55, v55, v55
	v_mul_f32_e32 v49, v49, v49
	v_mul_f32_e32 v51, v51, v51
	v_fmac_f32_e32 v53, v52, v52
	v_fmac_f32_e32 v55, v54, v54
	v_fmac_f32_e32 v49, v48, v48
	v_fmac_f32_e32 v51, v50, v50
	v_add_f32_e32 v53, v53, v55
	v_add_f32_e32 v53, v53, v49
	v_add_f32_e32 v53, v51, v53
	v_add_f32_e32 v194, v194, v53
	s_waitcnt vmcnt(26)
	v_pk_add_f32 v[44:45], v[44:45], v[220:221]
	v_pk_add_f32 v[46:47], v[46:47], v[222:223]
	v_pk_add_f32 v[40:41], v[40:41], v[224:225]
	v_pk_add_f32 v[42:43], v[42:43], v[226:227]
	v_cvt_pk_bf16_f32 v188, v44, v45
	v_cvt_pk_bf16_f32 v189, v46, v47
	v_cvt_pk_bf16_f32 v190, v40, v41
	v_cvt_pk_bf16_f32 v191, v42, v43
	v_cvt_pk_fp8_f32 v192, v44, v45
	v_cvt_pk_fp8_f32 v193, v40, v41
	v_cvt_pk_fp8_f32 v192, v46, v47 op_sel:[0,0,1]
	v_cvt_pk_fp8_f32 v193, v42, v43 op_sel:[0,0,1]
	v_add_u32_e32 v220, 0x90000, v251
	v_add_u32_e32 v221, 0x48000, v252
	global_store_dwordx4 v220, v[188:191], s[68:69] offset:0
	global_store_dwordx2 v221, v[192:193], s[14:15] offset:0
	v_mul_f32_e32 v45, v45, v45
	v_mul_f32_e32 v47, v47, v47
	v_mul_f32_e32 v41, v41, v41
	v_mul_f32_e32 v43, v43, v43
	v_fmac_f32_e32 v45, v44, v44
	v_fmac_f32_e32 v47, v46, v46
	v_fmac_f32_e32 v41, v40, v40
	v_fmac_f32_e32 v43, v42, v42
	v_add_f32_e32 v45, v45, v47
	v_add_f32_e32 v45, v45, v41
	v_add_f32_e32 v195, v43, v45
	s_waitcnt vmcnt(26)
	v_pk_add_f32 v[36:37], v[36:37], v[228:229]
	v_pk_add_f32 v[38:39], v[38:39], v[230:231]
	v_pk_add_f32 v[32:33], v[32:33], v[232:233]
	v_pk_add_f32 v[34:35], v[34:35], v[234:235]
	v_cvt_pk_bf16_f32 v188, v36, v37
	v_cvt_pk_bf16_f32 v189, v38, v39
	v_cvt_pk_bf16_f32 v190, v32, v33
	v_cvt_pk_bf16_f32 v191, v34, v35
	v_cvt_pk_fp8_f32 v192, v36, v37
	v_cvt_pk_fp8_f32 v193, v32, v33
	v_cvt_pk_fp8_f32 v192, v38, v39 op_sel:[0,0,1]
	v_cvt_pk_fp8_f32 v193, v34, v35 op_sel:[0,0,1]
	v_add_u32_e32 v228, 0x90000, v251
	v_add_u32_e32 v229, 0x48000, v252
	global_store_dwordx4 v228, v[188:191], s[68:69] offset:256
	global_store_dwordx2 v229, v[192:193], s[14:15] offset:128
	v_mul_f32_e32 v37, v37, v37
	v_mul_f32_e32 v39, v39, v39
	v_mul_f32_e32 v33, v33, v33
	v_mul_f32_e32 v35, v35, v35
	v_fmac_f32_e32 v37, v36, v36
	v_fmac_f32_e32 v39, v38, v38
	v_fmac_f32_e32 v33, v32, v32
	v_fmac_f32_e32 v35, v34, v34
	v_add_f32_e32 v37, v37, v39
	v_add_f32_e32 v37, v37, v33
	v_add_f32_e32 v37, v35, v37
	v_add_f32_e32 v195, v195, v37
	s_waitcnt vmcnt(22)
	v_pk_add_f32 v[28:29], v[28:29], v[236:237]
	v_pk_add_f32 v[30:31], v[30:31], v[238:239]
	v_pk_add_f32 v[24:25], v[24:25], v[240:241]
	v_pk_add_f32 v[26:27], v[26:27], v[242:243]
	v_cvt_pk_bf16_f32 v188, v28, v29
	v_cvt_pk_bf16_f32 v189, v30, v31
	v_cvt_pk_bf16_f32 v190, v24, v25
	v_cvt_pk_bf16_f32 v191, v26, v27
	v_cvt_pk_fp8_f32 v192, v28, v29
	v_cvt_pk_fp8_f32 v193, v24, v25
	v_cvt_pk_fp8_f32 v192, v30, v31 op_sel:[0,0,1]
	v_cvt_pk_fp8_f32 v193, v26, v27 op_sel:[0,0,1]
	v_add_u32_e32 v236, 0xa0000, v251
	v_add_u32_e32 v237, 0x50000, v252
	global_store_dwordx4 v236, v[188:191], s[68:69] offset:0
	global_store_dwordx2 v237, v[192:193], s[14:15] offset:0
	v_mul_f32_e32 v29, v29, v29
	v_mul_f32_e32 v31, v31, v31
	v_mul_f32_e32 v25, v25, v25
	v_mul_f32_e32 v27, v27, v27
	v_fmac_f32_e32 v29, v28, v28
	v_fmac_f32_e32 v31, v30, v30
	v_fmac_f32_e32 v25, v24, v24
	v_fmac_f32_e32 v27, v26, v26
	v_add_f32_e32 v29, v29, v31
	v_add_f32_e32 v29, v29, v25
	v_add_f32_e32 v196, v27, v29
	s_waitcnt vmcnt(22)
	v_pk_add_f32 v[20:21], v[20:21], v[244:245]
	v_pk_add_f32 v[22:23], v[22:23], v[246:247]
	v_pk_add_f32 v[16:17], v[16:17], v[168:169]
	v_pk_add_f32 v[18:19], v[18:19], v[170:171]
	v_cvt_pk_bf16_f32 v188, v20, v21
	v_cvt_pk_bf16_f32 v189, v22, v23
	v_cvt_pk_bf16_f32 v190, v16, v17
	v_cvt_pk_bf16_f32 v191, v18, v19
	v_cvt_pk_fp8_f32 v192, v20, v21
	v_cvt_pk_fp8_f32 v193, v16, v17
	v_cvt_pk_fp8_f32 v192, v22, v23 op_sel:[0,0,1]
	v_cvt_pk_fp8_f32 v193, v18, v19 op_sel:[0,0,1]
	v_add_u32_e32 v244, 0xa0000, v251
	v_add_u32_e32 v245, 0x50000, v252
	global_store_dwordx4 v244, v[188:191], s[68:69] offset:256
	global_store_dwordx2 v245, v[192:193], s[14:15] offset:128
	v_mul_f32_e32 v21, v21, v21
	v_mul_f32_e32 v23, v23, v23
	v_mul_f32_e32 v17, v17, v17
	v_mul_f32_e32 v19, v19, v19
	v_fmac_f32_e32 v21, v20, v20
	v_fmac_f32_e32 v23, v22, v22
	v_fmac_f32_e32 v17, v16, v16
	v_fmac_f32_e32 v19, v18, v18
	v_add_f32_e32 v21, v21, v23
	v_add_f32_e32 v21, v21, v17
	v_add_f32_e32 v21, v19, v21
	v_add_f32_e32 v196, v196, v21
	s_waitcnt vmcnt(18)
	v_pk_add_f32 v[12:13], v[12:13], v[172:173]
	v_pk_add_f32 v[14:15], v[14:15], v[174:175]
	v_pk_add_f32 v[8:9], v[8:9], v[176:177]
	v_pk_add_f32 v[10:11], v[10:11], v[178:179]
	v_cvt_pk_bf16_f32 v188, v12, v13
	v_cvt_pk_bf16_f32 v189, v14, v15
	v_cvt_pk_bf16_f32 v190, v8, v9
	v_cvt_pk_bf16_f32 v191, v10, v11
	v_cvt_pk_fp8_f32 v192, v12, v13
	v_cvt_pk_fp8_f32 v193, v8, v9
	v_cvt_pk_fp8_f32 v192, v14, v15 op_sel:[0,0,1]
	v_cvt_pk_fp8_f32 v193, v10, v11 op_sel:[0,0,1]
	v_add_u32_e32 v172, 0xb0000, v251
	v_add_u32_e32 v173, 0x58000, v252
	global_store_dwordx4 v172, v[188:191], s[68:69] offset:0
	global_store_dwordx2 v173, v[192:193], s[14:15] offset:0
	v_mul_f32_e32 v13, v13, v13
	v_mul_f32_e32 v15, v15, v15
	v_mul_f32_e32 v9, v9, v9
	v_mul_f32_e32 v11, v11, v11
	v_fmac_f32_e32 v13, v12, v12
	v_fmac_f32_e32 v15, v14, v14
	v_fmac_f32_e32 v9, v8, v8
	v_fmac_f32_e32 v11, v10, v10
	v_add_f32_e32 v13, v13, v15
	v_add_f32_e32 v13, v13, v9
	v_add_f32_e32 v249, v11, v13
	s_waitcnt vmcnt(18)
	v_pk_add_f32 v[4:5], v[4:5], v[180:181]
	v_pk_add_f32 v[6:7], v[6:7], v[182:183]
	v_pk_add_f32 v[0:1], v[0:1], v[184:185]
	v_pk_add_f32 v[2:3], v[2:3], v[186:187]
	v_cvt_pk_bf16_f32 v188, v4, v5
	v_cvt_pk_bf16_f32 v189, v6, v7
	v_cvt_pk_bf16_f32 v190, v0, v1
	v_cvt_pk_bf16_f32 v191, v2, v3
	v_cvt_pk_fp8_f32 v192, v4, v5
	v_cvt_pk_fp8_f32 v193, v0, v1
	v_cvt_pk_fp8_f32 v192, v6, v7 op_sel:[0,0,1]
	v_cvt_pk_fp8_f32 v193, v2, v3 op_sel:[0,0,1]
	v_add_u32_e32 v180, 0xb0000, v251
	v_add_u32_e32 v181, 0x58000, v252
	global_store_dwordx4 v180, v[188:191], s[68:69] offset:256
	global_store_dwordx2 v181, v[192:193], s[14:15] offset:128
	v_mul_f32_e32 v5, v5, v5
	v_mul_f32_e32 v7, v7, v7
	v_mul_f32_e32 v1, v1, v1
	v_mul_f32_e32 v3, v3, v3
	v_fmac_f32_e32 v5, v4, v4
	v_fmac_f32_e32 v7, v6, v6
	v_fmac_f32_e32 v1, v0, v0
	v_fmac_f32_e32 v3, v2, v2
	v_add_f32_e32 v5, v5, v7
	v_add_f32_e32 v5, v5, v1
	v_add_f32_e32 v5, v3, v5
	v_add_f32_e32 v249, v249, v5
	ds_bpermute_b32 v188, v254, v194
	ds_bpermute_b32 v189, v254, v195
	ds_bpermute_b32 v190, v254, v196
	ds_bpermute_b32 v191, v254, v249
	s_waitcnt lgkmcnt(0)
	v_add_f32_e32 v194, v194, v188
	v_add_f32_e32 v195, v195, v189
	v_add_f32_e32 v196, v196, v190
	v_add_f32_e32 v249, v249, v191
	ds_bpermute_b32 v188, v255, v194
	ds_bpermute_b32 v189, v255, v195
	ds_bpermute_b32 v190, v255, v196
	ds_bpermute_b32 v191, v255, v249
	s_waitcnt lgkmcnt(0)
	v_add_f32_e32 v194, v194, v188
	v_add_f32_e32 v195, v195, v189
	v_add_f32_e32 v196, v196, v190
	v_add_f32_e32 v249, v249, v191
	s_and_saveexec_b64 s[30:31], s[4:5]
	global_atomic_add_f32 v253, v194, s[12:13] offset:512
	global_atomic_add_f32 v253, v195, s[12:13] offset:576
	global_atomic_add_f32 v253, v196, s[12:13] offset:640
	global_atomic_add_f32 v253, v249, s[12:13] offset:704
	s_or_b64 exec, exec, s[30:31]
	s_andn2_b64 vcc, exec, s[6:7]
	s_mov_b64 s[6:7], -1
	s_cbranch_vccnz .LBB0_377
	s_andn2_b64 vcc, exec, s[10:11]
	s_cbranch_vccnz .LBB0_376
	s_barrier
	s_branch .LBB0_376
